# attnB fast path: LDS-DMA via saddr+voffset form (no 64-bit VALU address adds)
# speedup vs baseline: 1.0202x; 1.0202x over previous
.LBB0_1083:
	s_mov_b32 s48, s45
	s_mov_b32 s45, s12
	v_add_co_u32_e64 v164, s[12:13], s47, v162
	s_cmp_lg_u32 s82, 0
	s_cbranch_scc0 .Lold_it1
	s_waitcnt lgkmcnt(3)
	v_mfma_f32_32x32x16_bf16 v[48:63], v[184:187], v[128:131], v[48:63]
	s_add_u32 s84, s38, 0xffffa000
	s_addc_u32 s85, s39, -1
	s_add_u32 s86, s84, s58
	s_addc_u32 s87, s85, s59
	s_add_u32 s88, s84, s60
	s_addc_u32 s89, s85, s61
	s_add_u32 s90, s38, s52
	s_addc_u32 s91, s39, s53
	s_and_b64 s[18:19], s[10:11], exec
	s_cselect_b32 s88, s88, s90
	s_cselect_b32 s89, s89, s91
	s_cselect_b32 s18, s60, s46
	s_add_u32 s90, s38, s54
	s_addc_u32 s91, s39, s55
	s_add_i32 s34, s45, 16
	s_add_i32 s19, s74, s46
	s_xor_b64 s[42:43], s[40:41], -1
	ds_read_b128 v[216:219], v199 offset:64
	v_exp_f32_e32 v168, v0
	v_exp_f32_e32 v169, v1
	v_exp_f32_e32 v170, v2
	v_exp_f32_e32 v171, v3
	s_waitcnt lgkmcnt(3)
	v_mfma_f32_32x32x16_bf16 v[32:47], v[192:195], v[128:131], v[32:47]
	ds_read_b128 v[220:223], v199 offset:4672
	v_exp_f32_e32 v172, v4
	v_exp_f32_e32 v173, v5
	v_add_f32_e32 v98, v169, v168
	v_cvt_pk_bf16_f32 v128, v168, v169
	s_waitcnt lgkmcnt(3)
	v_mfma_f32_32x32x16_bf16 v[48:63], v[208:211], v[132:135], v[48:63]
	ds_read_b128 v[224:227], v199 offset:96
	v_exp_f32_e32 v174, v6
	v_exp_f32_e32 v175, v7
	v_add_f32_e32 v98, v170, v98
	v_add_f32_e32 v98, v171, v98
	v_cvt_pk_bf16_f32 v129, v170, v171
	s_waitcnt lgkmcnt(3)
	v_mfma_f32_32x32x16_bf16 v[32:47], v[212:215], v[132:135], v[32:47]
	ds_read_b128 v[228:231], v199 offset:4704
	v_exp_f32_e32 v176, v8
	v_exp_f32_e32 v177, v9
	v_add_f32_e32 v98, v172, v98
	v_add_f32_e32 v98, v173, v98
	s_waitcnt lgkmcnt(3)
	v_mfma_f32_32x32x16_bf16 v[48:63], v[216:219], v[136:139], v[48:63]
	ds_read_b128 v[232:235], v161 offset:15360
	v_cvt_pk_bf16_f32 v130, v172, v173
	v_exp_f32_e32 v178, v10
	v_exp_f32_e32 v179, v11
	v_add_f32_e32 v98, v174, v98
	s_waitcnt lgkmcnt(3)
	v_mfma_f32_32x32x16_bf16 v[32:47], v[220:223], v[136:139], v[32:47]
	s_mov_b32 m0, s74
	s_nop 0
	global_load_lds_dwordx4 v144, s[86:87]
	ds_read_b128 v[236:239], v161 offset:23040
	v_add_f32_e32 v98, v175, v98
	v_cvt_pk_bf16_f32 v131, v174, v175
	v_exp_f32_e32 v180, v12
	s_waitcnt lgkmcnt(3)
	v_mfma_f32_32x32x16_bf16 v[48:63], v[224:227], v[140:143], v[48:63]
	s_add_i32 m0, s18, 16
	s_nop 0
	global_load_lds_dwordx4 v144, s[88:89]
	ds_read_b128 v[240:243], v161 offset:15392
	v_exp_f32_e32 v181, v13
	v_add_f32_e32 v98, v176, v98
	v_add_f32_e32 v98, v177, v98
	s_waitcnt lgkmcnt(3)
	v_mfma_f32_32x32x16_bf16 v[32:47], v[228:231], v[140:143], v[32:47]
	s_add_i32 m0, s19, 0x400
	s_nop 0
	global_load_lds_dwordx4 v152, s[90:91]
	ds_read_b128 v[184:187], v161 offset:23072
	v_cvt_pk_bf16_f32 v132, v176, v177
	v_exp_f32_e32 v182, v14
	s_waitcnt lgkmcnt(3)
	v_mfma_f32_32x32x16_bf16 v[64:79], v[232:235], v[104:107], 0
	ds_read_b128 v[192:195], v161 offset:15424
	v_exp_f32_e32 v183, v15
	v_add_f32_e32 v98, v178, v98
	v_add_f32_e32 v98, v179, v98
	v_cvt_pk_bf16_f32 v133, v178, v179
	v_exp_f32_e32 v168, v16
	s_waitcnt lgkmcnt(3)
	v_mfma_f32_32x32x16_bf16 v[80:95], v[236:239], v[104:107], 0
	ds_read_b128 v[208:211], v161 offset:23104
	v_exp_f32_e32 v169, v17
	v_add_f32_e32 v98, v180, v98
	v_add_f32_e32 v98, v181, v98
	v_cvt_pk_bf16_f32 v134, v180, v181
	s_waitcnt lgkmcnt(3)
	v_mfma_f32_32x32x16_bf16 v[64:79], v[240:243], v[108:111], v[64:79]
	ds_read_b128 v[212:215], v161 offset:15456
	v_exp_f32_e32 v170, v18
	v_exp_f32_e32 v171, v19
	v_add_f32_e32 v98, v182, v98
	v_add_f32_e32 v98, v183, v98
	v_cvt_pk_bf16_f32 v135, v182, v183
	s_waitcnt lgkmcnt(3)
	v_mfma_f32_32x32x16_bf16 v[80:95], v[184:187], v[108:111], v[80:95]
	ds_read_b128 v[216:219], v161 offset:23136
	v_exp_f32_e32 v172, v20
	v_exp_f32_e32 v173, v21
	v_add_f32_e32 v98, v168, v98
	v_add_f32_e32 v98, v169, v98
	s_waitcnt lgkmcnt(3)
	v_mfma_f32_32x32x16_bf16 v[64:79], v[192:195], v[112:115], v[64:79]
	ds_read_b128 v[220:223], v161 offset:15488
	v_cvt_pk_bf16_f32 v136, v168, v169
	v_exp_f32_e32 v174, v22
	v_exp_f32_e32 v175, v23
	v_add_f32_e32 v98, v170, v98
	s_waitcnt lgkmcnt(3)
	v_mfma_f32_32x32x16_bf16 v[80:95], v[208:211], v[112:115], v[80:95]
	ds_read_b128 v[224:227], v161 offset:23168
	v_add_f32_e32 v98, v171, v98
	v_cvt_pk_bf16_f32 v137, v170, v171
	v_exp_f32_e32 v176, v24
	v_exp_f32_e32 v177, v25
	s_waitcnt lgkmcnt(3)
	v_mfma_f32_32x32x16_bf16 v[64:79], v[212:215], v[116:119], v[64:79]
	ds_read_b128 v[228:231], v161 offset:15520
	v_add_f32_e32 v98, v172, v98
	v_add_f32_e32 v98, v173, v98
	v_cvt_pk_bf16_f32 v138, v172, v173
	v_exp_f32_e32 v178, v26
	s_waitcnt lgkmcnt(3)
	v_mfma_f32_32x32x16_bf16 v[80:95], v[216:219], v[116:119], v[80:95]
	ds_read_b128 v[232:235], v161 offset:23200
	v_exp_f32_e32 v179, v27
	v_add_f32_e32 v98, v174, v98
	v_add_f32_e32 v98, v175, v98
	v_cvt_pk_bf16_f32 v139, v174, v175
	v_exp_f32_e32 v180, v28
	s_waitcnt lgkmcnt(3)
	v_mfma_f32_32x32x16_bf16 v[64:79], v[220:223], v[120:123], v[64:79]
	v_exp_f32_e32 v181, v29
	v_add_f32_e32 v98, v176, v98
	v_add_f32_e32 v98, v177, v98
	v_cvt_pk_bf16_f32 v140, v176, v177
	s_waitcnt lgkmcnt(2)
	v_mfma_f32_32x32x16_bf16 v[80:95], v[224:227], v[120:123], v[80:95]
	v_exp_f32_e32 v182, v30
	v_exp_f32_e32 v183, v31
	v_add_f32_e32 v98, v178, v98
	v_add_f32_e32 v98, v179, v98
	v_cvt_pk_bf16_f32 v141, v178, v179
	s_waitcnt lgkmcnt(1)
	v_mfma_f32_32x32x16_bf16 v[64:79], v[228:231], v[124:127], v[64:79]
	v_add_f32_e32 v98, v180, v98
	v_add_f32_e32 v98, v181, v98
	v_cvt_pk_bf16_f32 v142, v180, v181
	v_add_f32_e32 v98, v182, v98
	v_add_f32_e32 v167, v183, v98
	v_cvt_pk_bf16_f32 v143, v182, v183
	s_waitcnt lgkmcnt(0)
	v_mfma_f32_32x32x16_bf16 v[80:95], v[232:235], v[124:127], v[80:95]
	s_branch .LBB0_1094

.LBB0_1101:
	s_cmp_lt_i32 s47, -1
	s_cselect_b32 s82, 1, 0
	s_cmp_eq_u64 s[40:41], 0
	s_cselect_b32 s83, 1, 0
	s_and_b32 s82, s82, s83
	v_add_u32_e32 v199, s48, v158
	ds_read_b128 v[184:187], v199
	ds_read_b128 v[192:195], v199 offset:4608
	ds_read_b128 v[208:211], v199 offset:32
	ds_read_b128 v[212:215], v199 offset:4640
	s_waitcnt vmcnt(0)
	s_barrier
	s_cmp_lg_u32 s82, 0
	s_cbranch_scc0 .Lold_it2
	s_waitcnt lgkmcnt(3)
	v_mfma_f32_32x32x16_bf16 v[48:63], v[184:187], v[128:131], v[48:63]
	s_add_u32 s84, s38, 0xffffa000
	s_addc_u32 s85, s39, -1
	s_add_u32 s86, s38, s58
	s_addc_u32 s87, s39, s59
	s_add_u32 s88, s38, s60
	s_addc_u32 s89, s39, s61
	s_add_u32 s90, s84, s56
	s_addc_u32 s91, s85, s57
	s_and_b64 s[12:13], s[10:11], exec
	s_cselect_b32 s88, s88, s90
	s_cselect_b32 s89, s89, s91
	s_cselect_b32 s12, s75, s45
	s_add_u32 s90, s84, s62
	s_addc_u32 s91, s85, s63
	s_add_i32 s13, s34, s58
	s_xor_b64 s[42:43], s[40:41], -1
	ds_read_b128 v[216:219], v199 offset:64
	v_exp_f32_e32 v168, v64
	v_exp_f32_e32 v169, v65
	v_exp_f32_e32 v170, v66
	v_exp_f32_e32 v171, v67
	s_waitcnt lgkmcnt(3)
	v_mfma_f32_32x32x16_bf16 v[32:47], v[192:195], v[128:131], v[32:47]
	ds_read_b128 v[220:223], v199 offset:4672
	v_exp_f32_e32 v172, v68
	v_exp_f32_e32 v173, v69
	v_add_f32_e32 v98, v169, v168
	v_cvt_pk_bf16_f32 v128, v168, v169
	s_waitcnt lgkmcnt(3)
	v_mfma_f32_32x32x16_bf16 v[48:63], v[208:211], v[132:135], v[48:63]
	ds_read_b128 v[224:227], v199 offset:96
	v_exp_f32_e32 v174, v70
	v_exp_f32_e32 v175, v71
	v_add_f32_e32 v98, v170, v98
	v_add_f32_e32 v98, v171, v98
	v_cvt_pk_bf16_f32 v129, v170, v171
	s_waitcnt lgkmcnt(3)
	v_mfma_f32_32x32x16_bf16 v[32:47], v[212:215], v[132:135], v[32:47]
	ds_read_b128 v[228:231], v199 offset:4704
	v_exp_f32_e32 v176, v72
	v_exp_f32_e32 v177, v73
	v_add_f32_e32 v98, v172, v98
	v_add_f32_e32 v98, v173, v98
	s_waitcnt lgkmcnt(3)
	v_mfma_f32_32x32x16_bf16 v[48:63], v[216:219], v[136:139], v[48:63]
	ds_read_b128 v[232:235], v161
	v_cvt_pk_bf16_f32 v130, v172, v173
	v_exp_f32_e32 v178, v74
	v_exp_f32_e32 v179, v75
	v_add_f32_e32 v98, v174, v98
	s_waitcnt lgkmcnt(3)
	v_mfma_f32_32x32x16_bf16 v[32:47], v[220:223], v[136:139], v[32:47]
	s_add_i32 m0, s74, 0x3c00
	s_nop 0
	global_load_lds_dwordx4 v144, s[86:87]
	ds_read_b128 v[236:239], v161 offset:7680
	v_add_f32_e32 v98, v175, v98
	v_cvt_pk_bf16_f32 v131, v174, v175
	v_exp_f32_e32 v180, v76
	s_waitcnt lgkmcnt(3)
	v_mfma_f32_32x32x16_bf16 v[48:63], v[224:227], v[140:143], v[48:63]
	s_add_i32 m0, s12, 16
	s_nop 0
	global_load_lds_dwordx4 v144, s[88:89]
	ds_read_b128 v[240:243], v161 offset:32
	v_exp_f32_e32 v181, v77
	v_add_f32_e32 v98, v176, v98
	v_add_f32_e32 v98, v177, v98
	s_waitcnt lgkmcnt(3)
	v_mfma_f32_32x32x16_bf16 v[32:47], v[228:231], v[140:143], v[32:47]
	s_add_i32 m0, s13, 0x400
	s_nop 0
	global_load_lds_dwordx4 v144, s[90:91]
	ds_read_b128 v[184:187], v161 offset:7712
	v_cvt_pk_bf16_f32 v132, v176, v177
	v_exp_f32_e32 v182, v78
	s_waitcnt lgkmcnt(3)
	v_mfma_f32_32x32x16_bf16 v[0:15], v[232:235], v[104:107], 0
	ds_read_b128 v[192:195], v161 offset:64
	v_exp_f32_e32 v183, v79
	v_add_f32_e32 v98, v178, v98
	v_add_f32_e32 v98, v179, v98
	v_cvt_pk_bf16_f32 v133, v178, v179
	v_exp_f32_e32 v168, v80
	s_waitcnt lgkmcnt(3)
	v_mfma_f32_32x32x16_bf16 v[16:31], v[236:239], v[104:107], 0
	ds_read_b128 v[208:211], v161 offset:7744
	v_exp_f32_e32 v169, v81
	v_add_f32_e32 v98, v180, v98
	v_add_f32_e32 v98, v181, v98
	v_cvt_pk_bf16_f32 v134, v180, v181
	s_waitcnt lgkmcnt(3)
	v_mfma_f32_32x32x16_bf16 v[0:15], v[240:243], v[108:111], v[0:15]
	ds_read_b128 v[212:215], v161 offset:96
	v_exp_f32_e32 v170, v82
	v_exp_f32_e32 v171, v83
	v_add_f32_e32 v98, v182, v98
	v_add_f32_e32 v98, v183, v98
	v_cvt_pk_bf16_f32 v135, v182, v183
	s_waitcnt lgkmcnt(3)
	v_mfma_f32_32x32x16_bf16 v[16:31], v[184:187], v[108:111], v[16:31]
	ds_read_b128 v[216:219], v161 offset:7776
	v_exp_f32_e32 v172, v84
	v_exp_f32_e32 v173, v85
	v_add_f32_e32 v98, v168, v98
	v_add_f32_e32 v98, v169, v98
	s_waitcnt lgkmcnt(3)
	v_mfma_f32_32x32x16_bf16 v[0:15], v[192:195], v[112:115], v[0:15]
	ds_read_b128 v[220:223], v161 offset:128
	v_cvt_pk_bf16_f32 v136, v168, v169
	v_exp_f32_e32 v174, v86
	v_exp_f32_e32 v175, v87
	v_add_f32_e32 v98, v170, v98
	s_waitcnt lgkmcnt(3)
	v_mfma_f32_32x32x16_bf16 v[16:31], v[208:211], v[112:115], v[16:31]
	ds_read_b128 v[224:227], v161 offset:7808
	v_add_f32_e32 v98, v171, v98
	v_cvt_pk_bf16_f32 v137, v170, v171
	v_exp_f32_e32 v176, v88
	v_exp_f32_e32 v177, v89
	s_waitcnt lgkmcnt(3)
	v_mfma_f32_32x32x16_bf16 v[0:15], v[212:215], v[116:119], v[0:15]
	ds_read_b128 v[228:231], v161 offset:160
	v_add_f32_e32 v98, v172, v98
	v_add_f32_e32 v98, v173, v98
	v_cvt_pk_bf16_f32 v138, v172, v173
	v_exp_f32_e32 v178, v90
	s_waitcnt lgkmcnt(3)
	v_mfma_f32_32x32x16_bf16 v[16:31], v[216:219], v[116:119], v[16:31]
	ds_read_b128 v[232:235], v161 offset:7840
	v_exp_f32_e32 v179, v91
	v_add_f32_e32 v98, v174, v98
	v_add_f32_e32 v98, v175, v98
	v_cvt_pk_bf16_f32 v139, v174, v175
	v_exp_f32_e32 v180, v92
	s_waitcnt lgkmcnt(3)
	v_mfma_f32_32x32x16_bf16 v[0:15], v[220:223], v[120:123], v[0:15]
	v_exp_f32_e32 v181, v93
	v_add_f32_e32 v98, v176, v98
	v_add_f32_e32 v98, v177, v98
	v_cvt_pk_bf16_f32 v140, v176, v177
	s_waitcnt lgkmcnt(2)
	v_mfma_f32_32x32x16_bf16 v[16:31], v[224:227], v[120:123], v[16:31]
	v_exp_f32_e32 v182, v94
	v_exp_f32_e32 v183, v95
	v_add_f32_e32 v98, v178, v98
	v_add_f32_e32 v98, v179, v98
	v_cvt_pk_bf16_f32 v141, v178, v179
	s_waitcnt lgkmcnt(1)
	v_mfma_f32_32x32x16_bf16 v[0:15], v[228:231], v[124:127], v[0:15]
	v_add_f32_e32 v98, v180, v98
	v_add_f32_e32 v98, v181, v98
	v_cvt_pk_bf16_f32 v142, v180, v181
	v_add_f32_e32 v98, v182, v98
	v_add_f32_e32 v190, v183, v98
	v_cvt_pk_bf16_f32 v143, v182, v183
	s_waitcnt lgkmcnt(0)
	v_mfma_f32_32x32x16_bf16 v[16:31], v[232:235], v[124:127], v[16:31]
	s_branch .LBB0_1105
